# adds P7 tail: w_down rows prefetched before the A-fill
# speedup vs baseline: 1.0195x; 1.0033x over previous
.LBB0_1634:
	v_and_or_b32 v168, s12, -16, v1
	v_ashrrev_i32_e32 v169, 31, v168
	s_lshl_b32 s98, s14, 1
	v_lshlrev_b64 v[168:169], 14, v[168:169]
	s_and_b32 s98, s98, 0x2000
	v_or_b32_e32 v168, s98, v168
	v_lshl_add_u64 v[166:167], v[12:13], 0, v[168:169]
	global_load_dwordx4 v[102:105], v[166:167], off offset:-256
	global_load_dwordx4 v[106:109], v[166:167], off offset:-192
	global_load_dwordx4 v[110:113], v[166:167], off offset:-128
	global_load_dwordx4 v[114:117], v[166:167], off offset:-64
	global_load_dwordx4 v[118:121], v[166:167], off
	global_load_dwordx4 v[122:125], v[166:167], off offset:64
	global_load_dwordx4 v[126:129], v[166:167], off offset:128
	global_load_dwordx4 v[130:133], v[166:167], off offset:192
	v_lshl_add_u64 v[166:167], v[166:167], 0, s[8:9]
	global_load_dwordx4 v[134:137], v[166:167], off offset:-256
	global_load_dwordx4 v[138:141], v[166:167], off offset:-192
	global_load_dwordx4 v[142:145], v[166:167], off offset:-128
	global_load_dwordx4 v[146:149], v[166:167], off offset:-64
	global_load_dwordx4 v[150:153], v[166:167], off
	global_load_dwordx4 v[154:157], v[166:167], off offset:64
	global_load_dwordx4 v[158:161], v[166:167], off offset:128
	global_load_dwordx4 v[162:165], v[166:167], off offset:192
	s_mov_b32 s99, 0
	s_lshl_b32 s6, s16, 13
	s_and_b32 s6, s6, 0x2000
	v_lshl_add_u64 v[2:3], v[8:9], 0, s[6:7]
	v_lshl_add_u64 v[4:5], v[2:3], 0, v[14:15]
	global_load_dwordx4 v[38:41], v[2:3], off
	global_load_dwordx4 v[42:45], v[4:5], off
	v_lshl_add_u64 v[4:5], v[2:3], 0, v[16:17]
	v_lshl_add_u64 v[26:27], v[2:3], 0, v[18:19]
	global_load_dwordx4 v[46:49], v[4:5], off
	global_load_dwordx4 v[50:53], v[26:27], off
	v_lshl_add_u64 v[4:5], v[2:3], 0, v[20:21]
	v_lshl_add_u64 v[26:27], v[2:3], 0, v[22:23]
	global_load_dwordx4 v[54:57], v[4:5], off
	global_load_dwordx4 v[58:61], v[26:27], off
	v_lshl_add_u64 v[4:5], v[2:3], 0, v[24:25]
	global_load_dwordx4 v[62:65], v[4:5], off
	s_waitcnt vmcnt(6)
	ds_write_b128 v28, v[38:41]
	s_waitcnt vmcnt(5)
	ds_write_b128 v31, v[42:45]
	s_waitcnt vmcnt(4)
	ds_write_b128 v28, v[46:49] offset:16512
	s_waitcnt vmcnt(3)
	ds_write_b128 v32, v[50:53]
	s_waitcnt vmcnt(2)
	ds_write_b128 v28, v[54:57] offset:33024
	s_waitcnt vmcnt(1)
	ds_write_b128 v33, v[58:61]
	s_waitcnt vmcnt(0)
	ds_write_b128 v34, v[62:65]
	s_and_saveexec_b64 s[10:11], s[4:5]
	s_cbranch_execz .LBB0_1636
	v_lshl_add_u64 v[2:3], v[2:3], 0, v[6:7]
	global_load_dwordx4 v[2:5], v[2:3], off
	s_waitcnt vmcnt(0)
	ds_write_b128 v35, v[2:5]

.LBB0_1637:
	s_waitcnt vmcnt(0)
	s_cmp_eq_u32 s99, 0
	s_cbranch_scc0 .Lp7t_w1
	v_mov_b64_e32 v[38:39], v[102:103]
	v_mov_b64_e32 v[40:41], v[104:105]
	v_mov_b64_e32 v[42:43], v[106:107]
	v_mov_b64_e32 v[44:45], v[108:109]
	v_mov_b64_e32 v[46:47], v[110:111]
	v_mov_b64_e32 v[48:49], v[112:113]
	v_mov_b64_e32 v[50:51], v[114:115]
	v_mov_b64_e32 v[52:53], v[116:117]
	v_mov_b64_e32 v[54:55], v[118:119]
	v_mov_b64_e32 v[56:57], v[120:121]
	v_mov_b64_e32 v[58:59], v[122:123]
	v_mov_b64_e32 v[60:61], v[124:125]
	v_mov_b64_e32 v[62:63], v[126:127]
	v_mov_b64_e32 v[64:65], v[128:129]
	v_mov_b64_e32 v[66:67], v[130:131]
	v_mov_b64_e32 v[68:69], v[132:133]
	s_branch .Lp7t_go
.Lp7t_w1:
	v_mov_b64_e32 v[38:39], v[134:135]
	v_mov_b64_e32 v[40:41], v[136:137]
	v_mov_b64_e32 v[42:43], v[138:139]
	v_mov_b64_e32 v[44:45], v[140:141]
	v_mov_b64_e32 v[46:47], v[142:143]
	v_mov_b64_e32 v[48:49], v[144:145]
	v_mov_b64_e32 v[50:51], v[146:147]
	v_mov_b64_e32 v[52:53], v[148:149]
	v_mov_b64_e32 v[54:55], v[150:151]
	v_mov_b64_e32 v[56:57], v[152:153]
	v_mov_b64_e32 v[58:59], v[154:155]
	v_mov_b64_e32 v[60:61], v[156:157]
	v_mov_b64_e32 v[62:63], v[158:159]
	v_mov_b64_e32 v[64:65], v[160:161]
	v_mov_b64_e32 v[66:67], v[162:163]
	v_mov_b64_e32 v[68:69], v[164:165]
.Lp7t_go:
	s_add_i32 s99, s99, 1
	ds_read_b128 v[70:73], v37
	ds_read_b128 v[74:77], v37 offset:64
	ds_read_b128 v[78:81], v37 offset:128
	ds_read_b128 v[82:85], v37 offset:192
	ds_read_b128 v[86:89], v37 offset:256
	ds_read_b128 v[90:93], v37 offset:320
	ds_read_b128 v[94:97], v37 offset:384
	ds_read_b128 v[98:101], v37 offset:448
	s_waitcnt lgkmcnt(7)
	v_cndmask_b32_e64 v73, v73, 0, vcc
	v_cndmask_b32_e64 v72, v72, 0, vcc
	v_cndmask_b32_e64 v71, v71, 0, vcc
	v_cndmask_b32_e64 v70, v70, 0, vcc
	s_waitcnt lgkmcnt(6)
	v_cndmask_b32_e64 v77, v77, 0, vcc
	v_cndmask_b32_e64 v76, v76, 0, vcc
	v_cndmask_b32_e64 v75, v75, 0, vcc
	v_cndmask_b32_e64 v74, v74, 0, vcc
	s_waitcnt lgkmcnt(5)
	v_cndmask_b32_e64 v81, v81, 0, vcc
	v_cndmask_b32_e64 v80, v80, 0, vcc
	v_cndmask_b32_e64 v79, v79, 0, vcc
	v_cndmask_b32_e64 v78, v78, 0, vcc
	s_waitcnt lgkmcnt(4)
	v_cndmask_b32_e64 v85, v85, 0, vcc
	v_cndmask_b32_e64 v84, v84, 0, vcc
	v_cndmask_b32_e64 v83, v83, 0, vcc
	v_cndmask_b32_e64 v82, v82, 0, vcc
	s_addk_i32 s6, 0x100
	v_add_u32_e32 v37, 0x200, v37
	s_cmpk_gt_u32 s6, 0x1df
	v_lshl_add_u64 v[26:27], v[26:27], 0, s[8:9]
	s_waitcnt vmcnt(7)
	v_mfma_f32_16x16x32_bf16 v[2:5], v[70:73], v[38:41], v[2:5]
	s_waitcnt lgkmcnt(3)
	v_cndmask_b32_e64 v41, v89, 0, vcc
	v_cndmask_b32_e64 v40, v88, 0, vcc
	v_cndmask_b32_e64 v39, v87, 0, vcc
	s_waitcnt vmcnt(6)
	v_mfma_f32_16x16x32_bf16 v[2:5], v[74:77], v[42:45], v[2:5]
	v_cndmask_b32_e64 v38, v86, 0, vcc
	s_waitcnt lgkmcnt(2)
	v_cndmask_b32_e64 v45, v93, 0, vcc
	v_cndmask_b32_e64 v44, v92, 0, vcc
	s_waitcnt vmcnt(5)
	v_mfma_f32_16x16x32_bf16 v[2:5], v[78:81], v[46:49], v[2:5]
	v_cndmask_b32_e64 v43, v91, 0, vcc
	v_cndmask_b32_e64 v42, v90, 0, vcc
	s_waitcnt lgkmcnt(1)
	v_cndmask_b32_e64 v49, v97, 0, vcc
	s_waitcnt vmcnt(4)
	v_mfma_f32_16x16x32_bf16 v[2:5], v[82:85], v[50:53], v[2:5]
	v_cndmask_b32_e64 v48, v96, 0, vcc
	v_cndmask_b32_e64 v47, v95, 0, vcc
	v_cndmask_b32_e64 v46, v94, 0, vcc
	s_waitcnt vmcnt(3)
	v_mfma_f32_16x16x32_bf16 v[2:5], v[38:41], v[54:57], v[2:5]
	s_waitcnt lgkmcnt(0)
	v_cndmask_b32_e64 v41, v101, 0, vcc
	v_cndmask_b32_e64 v40, v100, 0, vcc
	v_cndmask_b32_e64 v39, v99, 0, vcc
	s_waitcnt vmcnt(2)
	v_mfma_f32_16x16x32_bf16 v[2:5], v[42:45], v[58:61], v[2:5]
	v_cndmask_b32_e64 v38, v98, 0, vcc
	s_waitcnt vmcnt(1)
	v_mfma_f32_16x16x32_bf16 v[2:5], v[46:49], v[62:65], v[2:5]
	s_waitcnt vmcnt(0)
	v_mfma_f32_16x16x32_bf16 v[2:5], v[38:41], v[66:69], v[2:5]
	s_cbranch_scc0 .LBB0_1637
	s_and_saveexec_b64 s[10:11], s[0:1]
	s_cbranch_execz .LBB0_1640
	s_nop 4
	ds_write2_b32 v36, v2, v3 offset1:16
	ds_write2_b32 v36, v4, v5 offset0:32 offset1:48
